# group sync: L1 invalidate issued before the poll loop instead of after it
# speedup vs baseline: 1.0119x; 1.0011x over previous
.LgA_have:
	s_cmp_eq_u32 s32, 1
	s_cbranch_scc0 .LgA_orig
	v_readlane_b32 s4, v252, 0
	s_nop 0
	s_and_b32 s4, s4, 63
	s_lshl_b32 s4, s4, 2
	s_add_u32 s4, s4, 0x13500000
	s_add_u32 s4, s40, s4
	s_addc_u32 s5, s41, 0
	s_lshl_b32 s6, s96, 3
	s_add_i32 s6, s6, 4
	v_mov_b32_e32 v1, 1
	v_mov_b32_e32 v2, s6
	s_mov_b64 exec, 1
	global_atomic_add v65, v1, s[4:5]
	buffer_inv sc1
	s_mov_b32 s27, 0

.LgA_done:
	s_waitcnt vmcnt(0)
	s_mov_b64 s[0:1], -1
	s_branch .LBB0_1238

.LBB0_1739:
	s_cmp_eq_u32 s32, 1
	s_cbranch_scc0 .LgB_orig
	v_readlane_b32 s4, v252, 0
	s_nop 0
	s_and_b32 s4, s4, 63
	s_lshl_b32 s4, s4, 2
	s_add_u32 s4, s4, 0x13500000
	s_add_u32 s4, s40, s4
	s_addc_u32 s5, s41, 0
	s_lshl_b32 s6, s96, 3
	s_add_i32 s6, s6, 8
	v_mov_b32_e32 v1, 1
	v_mov_b32_e32 v2, s6
	s_mov_b64 exec, 1
	global_atomic_add v65, v1, s[4:5]
	buffer_inv sc1
	s_mov_b32 s27, 0

.LgB_done:
	s_waitcnt vmcnt(0)
	s_mov_b64 exec, -1
	s_branch .Lg_to441
